# P5/P6 start stagger, four XCD groups 0/0.78/1.55/2.3 us
# baseline (speedup 1.0000x reference)
; #define LAS __attribute__((address_space(3)))
;     DI bool next(int i, Unit& u) const {
;         const long L = (long)i * G + c; if (L >= nwg) return false;
;         int wgid = (int)L; { const int q = nwg / NXCD, r = nwg % NXCD, xcd = wgid % NXCD, off = wgid / NXCD; wgid = (xcd < r ? xcd * (q + 1) : r * (q + 1) + (xcd - r) * q) + off; }
;         const int nig = WGM * nN, gid = wgid / nig, fm = gid * WGM, gsz = (nM - fm) < WGM ? (nM - fm) : WGM;
;         u.pm = fm + ((wgid % nig) % gsz); u.pn = (wgid % nig) / gsz; return true;
; __global__ void __launch_bounds__(512, 2) mega(Params p) {
;     ...
;     if (PH(5)) {
;         pg8::Gemm g; g.A0 = (const bf16_t*)(p.ws + WS_ZG); g.A1 = (const bf16_t*)(p.ws + WS_YB) - 2048; g.B0 = (const bf16_t*)(p.ws + WS_WAT); g.B1 = (const bf16_t*)(p.ws + WS_WBT) - 2048;
;         g.lda = DM; g.ldb = DM; g.M = S; g.N = DM; g.K = 2 * DM; g.ksplit = DM / 64;
;         pg8::StaticOrder so; so.init(g.M, g.N, (int)gridDim.x, (int)blockIdx.x);
;         EpiMergeMid e; e.ws = p.ws;
;         pg8::gemm_phase<EpiMergeMid>((LAS unsigned char*)shm, g, so, e);
.LBB0_431:
	s_or_b64 exec, exec, s[4:5]
	v_cmp_gt_i32_e32 vcc, 6, v0
	v_cmp_lt_i32_e64 s[4:5], 5, v1
	s_and_b64 s[4:5], vcc, s[4:5]
	s_and_saveexec_b64 s[6:7], s[4:5]
	s_cbranch_execz .LBB0_456
	s_and_b32 s90, s2, 3
.Lp5_stl:
	s_cmp_eq_u32 s90, 0
	s_cbranch_scc1 .Lp5_std
	s_sleep 21
	s_sub_u32 s90, s90, 1
	s_branch .Lp5_stl

; #define LAS __attribute__((address_space(3)))
;     DI bool next(int i, Unit& u) const {
;         const long L = (long)i * G + c; if (L >= nwg) return false;
;         int wgid = (int)L; { const int q = nwg / NXCD, r = nwg % NXCD, xcd = wgid % NXCD, off = wgid / NXCD; wgid = (xcd < r ? xcd * (q + 1) : r * (q + 1) + (xcd - r) * q) + off; }
;         const int nig = WGM * nN, gid = wgid / nig, fm = gid * WGM, gsz = (nM - fm) < WGM ? (nM - fm) : WGM;
;         u.pm = fm + ((wgid % nig) % gsz); u.pn = (wgid % nig) / gsz; return true;
; __global__ void __launch_bounds__(512, 2) mega(Params p) {
;     ...
;     if (PH(6)) {
;         pg8::Gemm g; g.A0 = (const bf16_t*)(p.ws + WS_MRG); g.A1 = g.A0; g.B0 = (const bf16_t*)(p.ws + WS_WOT); g.B1 = g.B0;
;         g.lda = DM; g.ldb = DM; g.M = S; g.N = DM; g.K = DM; g.ksplit = DM / 64;
;         pg8::StaticOrder so; so.init(g.M, g.N, (int)gridDim.x, (int)blockIdx.x);
;         EpiOut e; e.ws = p.ws;
;         pg8::gemm_phase<EpiOut>((LAS unsigned char*)shm, g, so, e);
.LBB0_506:
	s_or_b64 exec, exec, s[4:5]
	v_cmp_gt_i32_e32 vcc, 7, v0
	v_cmp_lt_i32_e64 s[4:5], 6, v1
	s_and_b64 s[4:5], vcc, s[4:5]
	s_and_saveexec_b64 s[8:9], s[4:5]
	s_cbranch_execz .LBB0_545
	s_and_b32 s90, s2, 3
